# S0 gated-norm partial sums: 64 serialized loads -> 32-deep pipelined; rs-cache fill loads issued in parallel, FFN-up conv weight loads hoisted above rs fill
# speedup vs baseline: 1.0429x; 1.0131x over previous
;     __device__ __forceinline__ void fused(f32x4 (&acc)[2][2][4][2], const pg8::Unit& u, int wr, int wc, int fr, int fq, LAS unsigned char* lds, int wid, int lane) const {
;     ...
;         if (ssq_in) {
;             const int r = tid & 255, hf = tid >> 8; const float* p = ssq_in + (size_t)(hf * 64) * M_ + (size_t)u.pm * 256 + r; float t = 0.f;
; #pragma unroll 16
;             for (int k = 0; k < 64; ++k) t += p[(size_t)k * M_];
;             S0[hf * 256 + r] = t;
;             asm volatile("s_waitcnt lgkmcnt(0)" ::: "memory"); __builtin_amdgcn_s_barrier(); asm volatile("" ::: "memory");
.LBB0_236:
	v_readlane_b32 s0, v255, 6
	s_waitcnt vmcnt(0)
	v_readlane_b32 s1, v255, 7
	v_mov_b32_e32 v2, s10
	s_andn2_b64 vcc, exec, s[0:1]
	v_cndmask_b32_e64 v4, 0, 1, s[0:1]
	s_movk_i32 s0, 0xffc0
	v_readlane_b32 s92, v254, 53
	v_readlane_b32 s80, v254, 55
	v_readlane_b32 s88, v254, 57
	v_cmp_ne_u32_e64 s[6:7], 1, v4
	v_bfi_b32 v4, s0, v2, v220
	v_readlane_b32 s93, v254, 54
	v_readlane_b32 s81, v254, 56
	v_readlane_b32 s89, v254, 58
	v_readlane_b32 s78, v254, 59
	s_mov_b32 s26, 0x9300000
	v_readlane_b32 s24, v255, 32
	v_readlane_b32 s25, v255, 31
	v_readlane_b32 s73, v255, 28
	v_readlane_b32 s74, v255, 33
	v_readlane_b32 s36, v255, 40
	s_barrier
	v_readlane_b32 s75, v255, 34
	s_cbranch_vccnz .LBB0_240
	v_readlane_b32 s0, v255, 38
	v_readlane_b32 s1, v255, 39
	s_mov_b32 s4, s0
	s_ashr_i32 s5, s0, 31
	v_writelane_b32 v255, s0, 38
	v_and_b32_e32 v5, 0xff, v4
	v_lshlrev_b32_e32 v2, 2, v5
	v_writelane_b32 v255, s1, 39
	s_lshl_b64 s[0:1], s[4:5], 16
	v_readlane_b32 s4, v255, 14
	v_readlane_b32 s5, v255, 15
	s_add_u32 s3, s4, s0
	s_addc_u32 s4, s5, s1
	s_ashr_i32 s75, s74, 31
	s_lshl_b64 s[0:1], s[74:75], 10
	s_add_u32 s0, s3, s0
	s_addc_u32 s1, s4, s1
	v_mov_b32_e32 v138, v2
	v_mov_b32_e32 v2, 0
	global_load_dword v144, v138, s[0:1]
	s_add_u32 s0, s0, 0x10000
	s_addc_u32 s1, s1, 0
	global_load_dword v145, v138, s[0:1]
	s_add_u32 s0, s0, 0x10000
	s_addc_u32 s1, s1, 0
	global_load_dword v146, v138, s[0:1]
	s_add_u32 s0, s0, 0x10000
	s_addc_u32 s1, s1, 0
	global_load_dword v147, v138, s[0:1]
	s_add_u32 s0, s0, 0x10000
	s_addc_u32 s1, s1, 0
	global_load_dword v148, v138, s[0:1]
	s_add_u32 s0, s0, 0x10000
	s_addc_u32 s1, s1, 0
	global_load_dword v149, v138, s[0:1]
	s_add_u32 s0, s0, 0x10000
	s_addc_u32 s1, s1, 0
	global_load_dword v150, v138, s[0:1]
	s_add_u32 s0, s0, 0x10000
	s_addc_u32 s1, s1, 0
	global_load_dword v151, v138, s[0:1]
	s_add_u32 s0, s0, 0x10000
	s_addc_u32 s1, s1, 0
	global_load_dword v152, v138, s[0:1]
	s_add_u32 s0, s0, 0x10000
	s_addc_u32 s1, s1, 0
	global_load_dword v153, v138, s[0:1]
	s_add_u32 s0, s0, 0x10000
	s_addc_u32 s1, s1, 0
	global_load_dword v154, v138, s[0:1]
	s_add_u32 s0, s0, 0x10000
	s_addc_u32 s1, s1, 0
	global_load_dword v155, v138, s[0:1]
	s_add_u32 s0, s0, 0x10000
	s_addc_u32 s1, s1, 0
	global_load_dword v156, v138, s[0:1]
	s_add_u32 s0, s0, 0x10000
	s_addc_u32 s1, s1, 0
	global_load_dword v157, v138, s[0:1]
	s_add_u32 s0, s0, 0x10000
	s_addc_u32 s1, s1, 0
	global_load_dword v158, v138, s[0:1]
	s_add_u32 s0, s0, 0x10000
	s_addc_u32 s1, s1, 0
	global_load_dword v159, v138, s[0:1]
	s_add_u32 s0, s0, 0x10000
	s_addc_u32 s1, s1, 0
	global_load_dword v160, v138, s[0:1]
	s_add_u32 s0, s0, 0x10000
	s_addc_u32 s1, s1, 0
	global_load_dword v161, v138, s[0:1]
	s_add_u32 s0, s0, 0x10000
	s_addc_u32 s1, s1, 0
	global_load_dword v162, v138, s[0:1]
	s_add_u32 s0, s0, 0x10000
	s_addc_u32 s1, s1, 0
	global_load_dword v163, v138, s[0:1]
	s_add_u32 s0, s0, 0x10000
	s_addc_u32 s1, s1, 0
	global_load_dword v164, v138, s[0:1]
	s_add_u32 s0, s0, 0x10000
	s_addc_u32 s1, s1, 0
	global_load_dword v165, v138, s[0:1]
	s_add_u32 s0, s0, 0x10000
	s_addc_u32 s1, s1, 0
	global_load_dword v166, v138, s[0:1]
	s_add_u32 s0, s0, 0x10000
	s_addc_u32 s1, s1, 0
	global_load_dword v167, v138, s[0:1]
	s_add_u32 s0, s0, 0x10000
	s_addc_u32 s1, s1, 0
	global_load_dword v168, v138, s[0:1]
	s_add_u32 s0, s0, 0x10000
	s_addc_u32 s1, s1, 0
	global_load_dword v169, v138, s[0:1]
	s_add_u32 s0, s0, 0x10000
	s_addc_u32 s1, s1, 0
	global_load_dword v176, v138, s[0:1]
	s_add_u32 s0, s0, 0x10000
	s_addc_u32 s1, s1, 0
	global_load_dword v177, v138, s[0:1]
	s_add_u32 s0, s0, 0x10000
	s_addc_u32 s1, s1, 0
	global_load_dword v178, v138, s[0:1]
	s_add_u32 s0, s0, 0x10000
	s_addc_u32 s1, s1, 0
	global_load_dword v179, v138, s[0:1]
	s_add_u32 s0, s0, 0x10000
	s_addc_u32 s1, s1, 0
	global_load_dword v180, v138, s[0:1]
	s_add_u32 s0, s0, 0x10000
	s_addc_u32 s1, s1, 0
	global_load_dword v181, v138, s[0:1]
	s_add_u32 s0, s0, 0x10000
	s_addc_u32 s1, s1, 0
	global_load_dword v182, v138, s[0:1]
	s_waitcnt vmcnt(32)
	v_add_f32_e32 v2, v2, v144
	s_add_u32 s0, s0, 0x10000
	s_addc_u32 s1, s1, 0
	global_load_dword v183, v138, s[0:1]
	s_waitcnt vmcnt(32)
	v_add_f32_e32 v2, v2, v145
	s_add_u32 s0, s0, 0x10000
	s_addc_u32 s1, s1, 0
	global_load_dword v184, v138, s[0:1]
	s_waitcnt vmcnt(32)
	v_add_f32_e32 v2, v2, v146
	s_add_u32 s0, s0, 0x10000
	s_addc_u32 s1, s1, 0
	global_load_dword v185, v138, s[0:1]
	s_waitcnt vmcnt(32)
	v_add_f32_e32 v2, v2, v147
	s_add_u32 s0, s0, 0x10000
	s_addc_u32 s1, s1, 0
	global_load_dword v186, v138, s[0:1]
	s_waitcnt vmcnt(32)
	v_add_f32_e32 v2, v2, v148
	s_add_u32 s0, s0, 0x10000
	s_addc_u32 s1, s1, 0
	global_load_dword v187, v138, s[0:1]
	s_waitcnt vmcnt(32)
	v_add_f32_e32 v2, v2, v149
	s_add_u32 s0, s0, 0x10000
	s_addc_u32 s1, s1, 0
	global_load_dword v188, v138, s[0:1]
	s_waitcnt vmcnt(32)
	v_add_f32_e32 v2, v2, v150
	s_add_u32 s0, s0, 0x10000
	s_addc_u32 s1, s1, 0
	global_load_dword v189, v138, s[0:1]
	s_waitcnt vmcnt(32)
;     __device__ __forceinline__ void fused(f32x4 (&acc)[2][2][4][2], const pg8::Unit& u, int wr, int wc, int fr, int fq, LAS unsigned char* lds, int wid, int lane) const {
;     ...
;             const int r = tid & 255, hf = tid >> 8; const float* p = ssq_in + (size_t)(hf * 64) * M_ + (size_t)u.pm * 256 + r; float t = 0.f;
; #pragma unroll 16
;             for (int k = 0; k < 64; ++k) t += p[(size_t)k * M_];
;             S0[hf * 256 + r] = t;
;             asm volatile("s_waitcnt lgkmcnt(0)" ::: "memory"); __builtin_amdgcn_s_barrier(); asm volatile("" ::: "memory");
	v_add_f32_e32 v2, v2, v151
	s_add_u32 s0, s0, 0x10000
	s_addc_u32 s1, s1, 0
	global_load_dword v190, v138, s[0:1]
	s_waitcnt vmcnt(32)
	v_add_f32_e32 v2, v2, v152
	s_add_u32 s0, s0, 0x10000
	s_addc_u32 s1, s1, 0
	global_load_dword v191, v138, s[0:1]
	s_waitcnt vmcnt(32)
	v_add_f32_e32 v2, v2, v153
	s_add_u32 s0, s0, 0x10000
	s_addc_u32 s1, s1, 0
	global_load_dword v192, v138, s[0:1]
	s_waitcnt vmcnt(32)
	v_add_f32_e32 v2, v2, v154
	s_add_u32 s0, s0, 0x10000
	s_addc_u32 s1, s1, 0
	global_load_dword v193, v138, s[0:1]
	s_waitcnt vmcnt(32)
	v_add_f32_e32 v2, v2, v155
	s_add_u32 s0, s0, 0x10000
	s_addc_u32 s1, s1, 0
	global_load_dword v194, v138, s[0:1]
	s_waitcnt vmcnt(32)
	v_add_f32_e32 v2, v2, v156
	s_add_u32 s0, s0, 0x10000
	s_addc_u32 s1, s1, 0
	global_load_dword v195, v138, s[0:1]
	s_waitcnt vmcnt(32)
	v_add_f32_e32 v2, v2, v157
	s_add_u32 s0, s0, 0x10000
	s_addc_u32 s1, s1, 0
	global_load_dword v196, v138, s[0:1]
	s_waitcnt vmcnt(32)
	v_add_f32_e32 v2, v2, v158
	s_add_u32 s0, s0, 0x10000
	s_addc_u32 s1, s1, 0
	global_load_dword v197, v138, s[0:1]
	s_waitcnt vmcnt(32)
	v_add_f32_e32 v2, v2, v159
	s_add_u32 s0, s0, 0x10000
	s_addc_u32 s1, s1, 0
	global_load_dword v198, v138, s[0:1]
	s_waitcnt vmcnt(32)
	v_add_f32_e32 v2, v2, v160
	s_add_u32 s0, s0, 0x10000
	s_addc_u32 s1, s1, 0
	global_load_dword v199, v138, s[0:1]
	s_waitcnt vmcnt(32)
	v_add_f32_e32 v2, v2, v161
	s_add_u32 s0, s0, 0x10000
	s_addc_u32 s1, s1, 0
	global_load_dword v200, v138, s[0:1]
	s_waitcnt vmcnt(32)
	v_add_f32_e32 v2, v2, v162
	s_add_u32 s0, s0, 0x10000
	s_addc_u32 s1, s1, 0
	global_load_dword v201, v138, s[0:1]
	s_waitcnt vmcnt(32)
	v_add_f32_e32 v2, v2, v163
	s_add_u32 s0, s0, 0x10000
	s_addc_u32 s1, s1, 0
	global_load_dword v202, v138, s[0:1]
	s_waitcnt vmcnt(32)
	v_add_f32_e32 v2, v2, v164
	s_add_u32 s0, s0, 0x10000
	s_addc_u32 s1, s1, 0
	global_load_dword v203, v138, s[0:1]
	s_waitcnt vmcnt(32)
	v_add_f32_e32 v2, v2, v165
	s_add_u32 s0, s0, 0x10000
	s_addc_u32 s1, s1, 0
	global_load_dword v204, v138, s[0:1]
	s_waitcnt vmcnt(32)
	v_add_f32_e32 v2, v2, v166
	s_add_u32 s0, s0, 0x10000
	s_addc_u32 s1, s1, 0
	global_load_dword v205, v138, s[0:1]
	s_waitcnt vmcnt(32)
	v_add_f32_e32 v2, v2, v167
	s_add_u32 s0, s0, 0x10000
	s_addc_u32 s1, s1, 0
	global_load_dword v225, v138, s[0:1]
	s_waitcnt vmcnt(32)
	v_add_f32_e32 v2, v2, v168
	s_add_u32 s0, s0, 0x10000
	s_addc_u32 s1, s1, 0
	global_load_dword v226, v138, s[0:1]
	s_waitcnt vmcnt(32)
	v_add_f32_e32 v2, v2, v169
	s_add_u32 s0, s0, 0x10000
	s_addc_u32 s1, s1, 0
	global_load_dword v227, v138, s[0:1]
	s_waitcnt vmcnt(32)
	v_add_f32_e32 v2, v2, v176
	s_add_u32 s0, s0, 0x10000
	s_addc_u32 s1, s1, 0
	global_load_dword v228, v138, s[0:1]
	s_waitcnt vmcnt(32)
	v_add_f32_e32 v2, v2, v177
	s_add_u32 s0, s0, 0x10000
	s_addc_u32 s1, s1, 0
	global_load_dword v229, v138, s[0:1]
	s_waitcnt vmcnt(32)
	v_add_f32_e32 v2, v2, v178
	s_add_u32 s0, s0, 0x10000
	s_addc_u32 s1, s1, 0
	global_load_dword v230, v138, s[0:1]
	s_waitcnt vmcnt(32)
	v_add_f32_e32 v2, v2, v179
	s_add_u32 s0, s0, 0x10000
	s_addc_u32 s1, s1, 0
	global_load_dword v231, v138, s[0:1]
	s_waitcnt vmcnt(32)
	v_add_f32_e32 v2, v2, v180
	s_add_u32 s0, s0, 0x10000
	s_addc_u32 s1, s1, 0
	global_load_dword v232, v138, s[0:1]
	s_waitcnt vmcnt(32)
	v_add_f32_e32 v2, v2, v181
	s_waitcnt vmcnt(31)
	v_add_f32_e32 v2, v2, v182
	s_waitcnt vmcnt(30)
	v_add_f32_e32 v2, v2, v183
	s_waitcnt vmcnt(29)
	v_add_f32_e32 v2, v2, v184
	s_waitcnt vmcnt(28)
	v_add_f32_e32 v2, v2, v185
	s_waitcnt vmcnt(27)
	v_add_f32_e32 v2, v2, v186
	s_waitcnt vmcnt(26)
	v_add_f32_e32 v2, v2, v187
	s_waitcnt vmcnt(25)
	v_add_f32_e32 v2, v2, v188
	s_waitcnt vmcnt(24)
	v_add_f32_e32 v2, v2, v189
	s_waitcnt vmcnt(23)
	v_add_f32_e32 v2, v2, v190
	s_waitcnt vmcnt(22)
	v_add_f32_e32 v2, v2, v191
	s_waitcnt vmcnt(21)
	v_add_f32_e32 v2, v2, v192
	s_waitcnt vmcnt(20)
	v_add_f32_e32 v2, v2, v193
	s_waitcnt vmcnt(19)
	v_add_f32_e32 v2, v2, v194
	s_waitcnt vmcnt(18)
	v_add_f32_e32 v2, v2, v195
	s_waitcnt vmcnt(17)
	v_add_f32_e32 v2, v2, v196
	s_waitcnt vmcnt(16)
	v_add_f32_e32 v2, v2, v197
	s_waitcnt vmcnt(15)
	v_add_f32_e32 v2, v2, v198
	s_waitcnt vmcnt(14)
	v_add_f32_e32 v2, v2, v199
	s_waitcnt vmcnt(13)
	v_add_f32_e32 v2, v2, v200
	s_waitcnt vmcnt(12)
	v_add_f32_e32 v2, v2, v201
	s_waitcnt vmcnt(11)
	v_add_f32_e32 v2, v2, v202
	s_waitcnt vmcnt(10)
	v_add_f32_e32 v2, v2, v203
	s_waitcnt vmcnt(9)
	v_add_f32_e32 v2, v2, v204
	s_waitcnt vmcnt(8)
	v_add_f32_e32 v2, v2, v205
	s_waitcnt vmcnt(7)
	v_add_f32_e32 v2, v2, v225
	s_waitcnt vmcnt(6)
	v_add_f32_e32 v2, v2, v226
	s_waitcnt vmcnt(5)
	v_add_f32_e32 v2, v2, v227
	s_waitcnt vmcnt(4)
	v_add_f32_e32 v2, v2, v228
	s_waitcnt vmcnt(3)
	v_add_f32_e32 v2, v2, v229
	s_waitcnt vmcnt(2)
	v_add_f32_e32 v2, v2, v230
	s_waitcnt vmcnt(1)
	v_add_f32_e32 v2, v2, v231
	s_waitcnt vmcnt(0)
	v_add_f32_e32 v2, v2, v232
	s_lshl_b32 s0, s2, 10
	s_add_i32 s0, s0, 0
	v_lshl_add_u32 v5, v5, 2, s0
	ds_write_b32 v5, v2 offset:8192
	s_waitcnt lgkmcnt(0)
	s_barrier

; __device__ __forceinline__ float rsx(const float* ssqx, int row) { const f32x4 p = *(const f32x4*)(ssqx + (size_t)row * 4); return rsqrtf(((p[0] + p[1]) + (p[2] + p[3])) * (1.0f / 1024.f) + EPS_); }
; __device__ __forceinline__ void rs_cache_fill(RsCache& C, const float* ssqx, int pm, int wr, int lane) {
;     if (C.pm != pm) {
;         C.tab[lane] = rsx(ssqx, pm * 256 + wr * 64 + lane); C.tab[64 + lane] = rsx(ssqx, pm * 256 + 128 + wr * 64 + lane);
;         C.pm = pm;
;     }
; }
;     __device__ __forceinline__ void fast(const f32x4 (&acc)[2][2][4][2], const pg8::Unit& u, int wr, int wc, int fr, int fq, RsCache& rsc) const {
;         asm volatile("" : "+v"(fr), "+v"(fq));
;         rs_cache_fill(rsc, rs, u.pm, wr, fq * 16 + fr);
;         typedef float f32x2 __attribute__((ext_vector_type(2)));
;         const int ch = u.pn * 128 + wc * 32 + 8 * fq;
;         f32x2 w0[4], w1[4], w2[4], bb[4];
; #pragma unroll
;         for (int h = 0; h < 2; ++h) { const f32x4 t0 = *(const f32x4*)(cw + ch + 4 * h), t1 = *(const f32x4*)(cw + FH + ch + 4 * h), t2 = *(const f32x4*)(cw + 2 * FH + ch + 4 * h), t3 = *(const f32x4*)(cb + ch + 4 * h);
;             w0[2 * h] = (f32x2){t0[0], t0[1]}; w0[2 * h + 1] = (f32x2){t0[2], t0[3]}; w1[2 * h] = (f32x2){t1[0], t1[1]}; w1[2 * h + 1] = (f32x2){t1[2], t1[3]};
;             w2[2 * h] = (f32x2){t2[0], t2[1]}; w2[2 * h + 1] = (f32x2){t2[2], t2[3]}; bb[2 * h] = (f32x2){t3[0], t3[1]}; bb[2 * h + 1] = (f32x2){t3[2], t3[3]}; }
.LBB0_262:
	v_mov_b32_e32 v186, v220
	v_mov_b32_e32 v58, v175
	s_lshl_b32 s0, s2, 7
	s_or_b32 s0, s0, s97
	v_lshl_add_u32 v184, v58, 3, s0
	v_ashrrev_i32_e32 v185, 31, v184
	v_readlane_b32 s0, v255, 22
	v_lshlrev_b64 v[58:59], 2, v[184:185]
	v_readlane_b32 s1, v255, 23
	v_lshl_add_u32 v223, v186, 2, s68
	v_cmp_lt_i32_e64 s[6:7], 1, v186
	v_lshl_add_u64 v[60:61], s[0:1], 0, v[58:59]
	v_readlane_b32 s0, v255, 20
	v_readlane_b32 s1, v255, 21
	s_nop 0
	s_nop 0
	v_lshl_add_u64 v[66:67], s[0:1], 0, v[58:59]
	v_readlane_b32 s0, v255, 24
	v_readlane_b32 s1, v255, 25
	s_nop 1
	v_lshl_add_u64 v[74:75], s[0:1], 0, v[58:59]
	v_readlane_b32 s0, v255, 18
	v_readlane_b32 s1, v255, 19
	s_nop 1
	v_lshl_add_u64 v[102:103], s[0:1], 0, v[58:59]
	global_load_dwordx4 v[70:73], v[60:61], off offset:16
	global_load_dwordx4 v[90:93], v[60:61], off
	s_nop 0
	global_load_dwordx4 v[58:61], v[66:67], off offset:16
	global_load_dwordx4 v[94:97], v[66:67], off
	s_nop 0
	global_load_dwordx4 v[66:69], v[74:75], off offset:16
	global_load_dwordx4 v[98:101], v[74:75], off
	s_nop 0
	global_load_dwordx4 v[74:77], v[102:103], off offset:16
	s_nop 0
	global_load_dwordx4 v[102:105], v[102:103], off
	s_cmp_lg_u32 s3, s10
	s_mov_b64 s[0:1], -1
	s_cbranch_scc0 .LBB0_264
	s_lshl_b32 s0, s10, 8
	v_readlane_b32 s1, v255, 6
	v_lshl_add_u32 v196, v175, 4, v220
	s_add_i32 s3, s0, s1
	v_add_u32_e32 v198, s3, v196
	v_readlane_b32 s0, v253, 18
	v_ashrrev_i32_e32 v199, 31, v198
	v_readlane_b32 s1, v253, 19
	v_lshl_add_u32 v196, v196, 2, s68
	s_nop 0
	v_lshl_add_u64 v[200:201], v[198:199], 4, s[0:1]
	global_load_dwordx4 v[188:191], v[200:201], off
	global_load_dwordx4 v[192:195], v[200:201], off offset:2048
	s_mov_b32 s0, 0x3a800000
	s_waitcnt vmcnt(1)
	v_mov_b32_e32 v198, v189
	v_mov_b32_e32 v199, v190
	v_mov_b32_e32 v189, v191
	v_pk_add_f32 v[198:199], v[198:199], v[188:189]
	s_waitcnt vmcnt(0)
	v_mov_b32_e32 v200, v193
	v_mov_b32_e32 v201, v194
	v_mov_b32_e32 v193, v195
	v_pk_add_f32 v[200:201], v[200:201], v[192:193]
	v_mov_b32_e32 v189, v198
	v_mov_b32_e32 v188, v200
	v_mov_b32_e32 v198, v201
	v_pk_add_f32 v[200:201], v[188:189], v[198:199]
	s_nop 0
	v_pk_fma_f32 v[200:201], v[200:201], s[0:1], v[170:171] op_sel_hi:[1,0,0]
	s_mov_b32 s0, 0x800000
	v_mul_f32_e32 v188, 0x4b800000, v201
	v_cmp_gt_f32_e32 vcc, s0, v200
	v_cmp_gt_f32_e64 s[0:1], s0, v201
	s_nop 1
	v_cndmask_b32_e64 v201, v201, v188, s[0:1]
	v_rsq_f32_e32 v201, v201
	s_nop 0
	v_mul_f32_e32 v188, 0x45800000, v201
	v_cndmask_b32_e64 v201, v201, v188, s[0:1]
	v_mul_f32_e32 v188, 0x4b800000, v200
	v_cndmask_b32_e32 v200, v200, v188, vcc
	v_rsq_f32_e32 v200, v200
	s_mov_b64 s[0:1], 0
	v_mul_f32_e32 v188, 0x45800000, v200
	v_cndmask_b32_e32 v200, v200, v188, vcc
	ds_write2st64_b32 v196, v201, v200 offset1:1

; __device__ __forceinline__ unsigned pk2(float lo, float hi) { unsigned r; asm volatile("v_cvt_pk_bf16_f32 %0, %1, %2" : "=v"(r) : "v"(lo), "v"(hi)); return r; }
; template <int CTRL> __device__ __forceinline__ float dppz(float x) { return __builtin_bit_cast(float, __builtin_amdgcn_update_dpp(0, __builtin_bit_cast(int, x), CTRL, 0xf, 0xf, true)); }
;     __device__ __forceinline__ void fast(const f32x4 (&acc)[2][2][4][2], const pg8::Unit& u, int wr, int wc, int fr, int fq, RsCache& rsc) const {
;     ...
;             for (int m = 0; m < 4; ++m) {
;                 const int row = rowb + m * 16 + fr; const float s = rsc.tab[ai * 64 + m * 16 + fr]; const f32x2 s2 = (f32x2){s, s};
;                 f32x2 g[4], o[4], v[4];
; #pragma unroll
;                 for (int cp = 0; cp < 4; ++cp) { const int n = cp >> 1, e0 = (cp & 1) * 2;
;                     g[cp] = (f32x2){acc[ai][0][m][n][e0], acc[ai][0][m][n][e0 + 1]} * s2; v[cp] = (f32x2){acc[ai][1][m][n][e0], acc[ai][1][m][n][e0 + 1]} * s2; }
; #pragma unroll
;                 for (int cp = 0; cp < 4; ++cp) {
;                     f32x2 p1 = (f32x2){dppz<0x111>(g[cp].x), dppz<0x111>(g[cp].y)}, p2 = (f32x2){dppz<0x112>(g[cp].x), dppz<0x112>(g[cp].y)};
;                     if (m > 0) { p1 += (f32x2){dppz<0x10F>(gp[cp].x), dppz<0x10F>(gp[cp].y)}; p2 += (f32x2){dppz<0x10E>(gp[cp].x), dppz<0x10E>(gp[cp].y)}; }
;                     const f32x2 gv = bb[cp] + w0[cp] * p2 + w1[cp] * p1 + w2[cp] * g[cp];
;                     const f32x2 ea = gv * (-1.44269504089f);
;                     f32x2 ex; ex.x = __builtin_amdgcn_exp2f(ea.x); ex.y = __builtin_amdgcn_exp2f(ea.y);
;                     const f32x2 dn = ex + 1.0f;
;                     f32x2 rc; rc.x = __builtin_amdgcn_rcpf(dn.x); rc.y = __builtin_amdgcn_rcpf(dn.y);
;                     o[cp] = (gv * rc) * v[cp];
;                 }
;                 if (m > 0 || fr >= 2) { uint4 w; w.x = pk2(o[0].x, o[0].y); w.y = pk2(o[1].x, o[1].y); w.z = pk2(o[2].x, o[2].y); w.w = pk2(o[3].x, o[3].y); *(uint4*)(act + (size_t)row * FH + ch) = w; }
.LBB0_266:
	v_add_u32_e32 v224, s3, v186
	ds_read_b32 v172, v223
	s_waitcnt lgkmcnt(0)
	v_pk_mul_f32 v[188:189], v[166:167], v[172:173] op_sel_hi:[1,0]
	v_pk_mul_f32 v[190:191], v[158:159], v[172:173] op_sel_hi:[1,0]
	v_pk_mul_f32 v[166:167], v[168:169], v[172:173] op_sel_hi:[1,0]
	v_pk_mul_f32 v[168:169], v[160:161], v[172:173] op_sel_hi:[1,0]
	v_pk_mul_f32 v[160:161], v[162:163], v[172:173] op_sel_hi:[1,0]
	v_pk_mul_f32 v[158:159], v[164:165], v[172:173] op_sel_hi:[1,0]
	v_pk_mul_f32 v[162:163], v[154:155], v[172:173] op_sel_hi:[1,0]
	v_pk_mul_f32 v[156:157], v[156:157], v[172:173] op_sel_hi:[1,0]
	v_mov_b32_dpp v192, v188 row_shr:1 row_mask:0xf bank_mask:0xf bound_ctrl:1
	v_mov_b32_dpp v193, v189 row_shr:1 row_mask:0xf bank_mask:0xf bound_ctrl:1
	v_mov_b32_dpp v194, v188 row_shr:2 row_mask:0xf bank_mask:0xf bound_ctrl:1
	v_mov_b32_dpp v195, v189 row_shr:2 row_mask:0xf bank_mask:0xf bound_ctrl:1
	v_mov_b32_dpp v196, v166 row_shr:1 row_mask:0xf bank_mask:0xf bound_ctrl:1
	v_mov_b32_dpp v197, v167 row_shr:1 row_mask:0xf bank_mask:0xf bound_ctrl:1
	v_mov_b32_dpp v198, v166 row_shr:2 row_mask:0xf bank_mask:0xf bound_ctrl:1
	v_mov_b32_dpp v199, v167 row_shr:2 row_mask:0xf bank_mask:0xf bound_ctrl:1
	v_mov_b32_dpp v200, v160 row_shr:1 row_mask:0xf bank_mask:0xf bound_ctrl:1
	v_mov_b32_dpp v201, v161 row_shr:1 row_mask:0xf bank_mask:0xf bound_ctrl:1
	v_mov_b32_dpp v202, v160 row_shr:2 row_mask:0xf bank_mask:0xf bound_ctrl:1
	v_mov_b32_dpp v203, v161 row_shr:2 row_mask:0xf bank_mask:0xf bound_ctrl:1
	v_mov_b32_dpp v154, v158 row_shr:1 row_mask:0xf bank_mask:0xf bound_ctrl:1
	v_mov_b32_dpp v155, v159 row_shr:1 row_mask:0xf bank_mask:0xf bound_ctrl:1
	v_mov_b32_dpp v164, v158 row_shr:2 row_mask:0xf bank_mask:0xf bound_ctrl:1
	v_mov_b32_dpp v165, v159 row_shr:2 row_mask:0xf bank_mask:0xf bound_ctrl:1
	s_and_saveexec_b64 s[0:1], s[6:7]
	v_readlane_b32 s78, v254, 59
	s_cbranch_execz .LBB0_268
	s_waitcnt vmcnt(0)
	v_pk_fma_f32 v[194:195], v[90:91], v[194:195], v[102:103]
	v_pk_fma_f32 v[164:165], v[72:73], v[164:165], v[76:77]
	v_pk_fma_f32 v[172:173], v[70:71], v[202:203], v[74:75]
	v_pk_fma_f32 v[198:199], v[92:93], v[198:199], v[104:105]
	v_pk_fma_f32 v[192:193], v[94:95], v[192:193], v[194:195]
	v_pk_fma_f32 v[154:155], v[60:61], v[154:155], v[164:165]
	v_pk_fma_f32 v[172:173], v[58:59], v[200:201], v[172:173]
	s_mov_b32 s2, 0xbfb8aa3b
	v_pk_fma_f32 v[196:197], v[96:97], v[196:197], v[198:199]
	v_pk_fma_f32 v[192:193], v[98:99], v[188:189], v[192:193]
	v_pk_fma_f32 v[154:155], v[68:69], v[158:159], v[154:155]
	v_pk_fma_f32 v[172:173], v[66:67], v[160:161], v[172:173]
	v_pk_fma_f32 v[196:197], v[100:101], v[166:167], v[196:197]
	v_pk_mul_f32 v[194:195], v[192:193], s[2:3] op_sel_hi:[1,0]
	v_pk_mul_f32 v[164:165], v[154:155], s[2:3] op_sel_hi:[1,0]
	v_pk_mul_f32 v[200:201], v[172:173], s[2:3] op_sel_hi:[1,0]
	v_pk_mul_f32 v[198:199], v[196:197], s[2:3] op_sel_hi:[1,0]
	v_exp_f32_e32 v194, v194
	v_exp_f32_e32 v195, v195
	v_exp_f32_e32 v164, v164
	v_exp_f32_e32 v165, v165
	v_exp_f32_e32 v200, v200
	v_exp_f32_e32 v201, v201
	v_exp_f32_e32 v198, v198
	v_exp_f32_e32 v199, v199
	v_pk_add_f32 v[194:195], v[194:195], 1.0 op_sel_hi:[1,0]
	v_pk_add_f32 v[164:165], v[164:165], 1.0 op_sel_hi:[1,0]
	v_pk_add_f32 v[200:201], v[200:201], 1.0 op_sel_hi:[1,0]
	v_pk_add_f32 v[198:199], v[198:199], 1.0 op_sel_hi:[1,0]
	v_rcp_f32_e32 v194, v194
	v_rcp_f32_e32 v195, v195
	v_rcp_f32_e32 v164, v164
	v_rcp_f32_e32 v165, v165
	v_rcp_f32_e32 v200, v200
	v_rcp_f32_e32 v201, v201
	v_rcp_f32_e32 v198, v198
	v_rcp_f32_e32 v199, v199
	v_pk_mul_f32 v[192:193], v[192:193], v[194:195]
	v_pk_mul_f32 v[154:155], v[154:155], v[164:165]
	v_readlane_b32 s8, v253, 16
	v_pk_mul_f32 v[172:173], v[172:173], v[200:201]
	v_pk_mul_f32 v[196:197], v[196:197], v[198:199]
	v_pk_mul_f32 v[192:193], v[190:191], v[192:193]
	v_pk_mul_f32 v[154:155], v[156:157], v[154:155]
	v_readlane_b32 s9, v253, 17
	v_pk_mul_f32 v[172:173], v[162:163], v[172:173]
	v_pk_mul_f32 v[196:197], v[168:169], v[196:197]
	v_cvt_pk_bf16_f32 v192, v192, v193
	s_nop 0
	v_cvt_pk_bf16_f32 v193, v196, v197
	v_cvt_pk_bf16_f32 v194, v172, v173
	v_cvt_pk_bf16_f32 v195, v154, v155
	v_mov_b64_e32 v[154:155], s[8:9]
	v_mad_i64_i32 v[154:155], s[8:9], v224, s93, v[154:155]
	v_lshl_add_u64 v[154:155], v[184:185], 1, v[154:155]
	global_store_dwordx4 v[154:155], v[192:195], off sc1

; __device__ __forceinline__ float rsx(const float* ssqx, int row) { const f32x4 p = *(const f32x4*)(ssqx + (size_t)row * 4); return rsqrtf(((p[0] + p[1]) + (p[2] + p[3])) * (1.0f / 1024.f) + EPS_); }
; __device__ __forceinline__ void rs_cache_fill(RsCache& C, const float* ssqx, int pm, int wr, int lane) {
;     if (C.pm != pm) {
;         C.tab[lane] = rsx(ssqx, pm * 256 + wr * 64 + lane); C.tab[64 + lane] = rsx(ssqx, pm * 256 + 128 + wr * 64 + lane);
;         C.pm = pm;
;     }
; }
.LBB0_300:
	v_mov_b32_e32 v146, v149
	v_mov_b32_e32 v147, v152
	s_cmp_lg_u32 s36, s88
	s_mov_b64 s[0:1], -1
	s_cbranch_scc0 .LBB0_302
	s_lshl_b32 s36, s88, 8
	v_lshl_add_u32 v148, v146, 4, v147
	s_add_i32 s0, s36, s92
	v_add_u32_e32 v150, s0, v148
	v_readlane_b32 s0, v253, 18
	v_ashrrev_i32_e32 v151, 31, v150
	v_readlane_b32 s1, v253, 19
	v_lshl_add_u32 v148, v148, 2, s89
	s_nop 0
	v_lshl_add_u64 v[150:151], v[150:151], 4, s[0:1]
	global_load_dwordx4 v[156:159], v[150:151], off
	global_load_dwordx4 v[162:165], v[150:151], off offset:2048
	s_mov_b32 s0, 0x3a800000
	s_waitcnt vmcnt(1)
	v_mov_b32_e32 v160, v157
	v_mov_b32_e32 v161, v158
	v_mov_b32_e32 v157, v159
	v_pk_add_f32 v[160:161], v[160:161], v[156:157]
	s_waitcnt vmcnt(0)
	v_mov_b32_e32 v150, v163
	v_mov_b32_e32 v151, v164
	v_mov_b32_e32 v163, v165
	v_pk_add_f32 v[150:151], v[150:151], v[162:163]
	v_mov_b32_e32 v157, v160
	v_mov_b32_e32 v156, v150
	v_mov_b32_e32 v160, v151
	v_pk_add_f32 v[150:151], v[156:157], v[160:161]
	s_nop 0
	v_pk_fma_f32 v[150:151], v[150:151], s[0:1], v[170:171] op_sel_hi:[1,0,0]
	s_mov_b32 s0, 0x800000
	v_mul_f32_e32 v155, 0x4b800000, v151
	v_cmp_gt_f32_e32 vcc, s0, v150
	v_cmp_gt_f32_e64 s[0:1], s0, v151
	s_nop 1
	v_cndmask_b32_e64 v151, v151, v155, s[0:1]
	v_rsq_f32_e32 v151, v151
	s_nop 0
	v_mul_f32_e32 v155, 0x45800000, v151
	v_cndmask_b32_e64 v151, v151, v155, s[0:1]
	v_mul_f32_e32 v155, 0x4b800000, v150
	v_cndmask_b32_e32 v150, v150, v155, vcc
	v_rsq_f32_e32 v150, v150
	s_mov_b64 s[0:1], 0
	v_mul_f32_e32 v155, 0x45800000, v150
	v_cndmask_b32_e32 v150, v150, v155, vcc
	ds_write2st64_b32 v148, v151, v150 offset1:1

; __device__ __forceinline__ float rsx(const float* ssqx, int row) { const f32x4 p = *(const f32x4*)(ssqx + (size_t)row * 4); return rsqrtf(((p[0] + p[1]) + (p[2] + p[3])) * (1.0f / 1024.f) + EPS_); }
; __device__ __forceinline__ void rs_cache_fill(RsCache& C, const float* ssqx, int pm, int wr, int lane) {
;     if (C.pm != pm) {
;         C.tab[lane] = rsx(ssqx, pm * 256 + wr * 64 + lane); C.tab[64 + lane] = rsx(ssqx, pm * 256 + 128 + wr * 64 + lane);
;         C.pm = pm;
;     }
; }
.LBB0_331:
	v_mov_b32_e32 v2, v168
	v_mov_b32_e32 v177, v169
	s_cmp_lg_u32 s2, s15
	s_mov_b64 s[0:1], -1
	s_mov_b32 s10, 0x41a00000
	s_mov_b32 s11, 0x3f2aaaab
	s_mov_b32 s26, 0x3f317218
	s_cbranch_scc0 .LBB0_333
	s_lshl_b32 s2, s15, 8
	v_lshl_add_u32 v146, v2, 4, v177
	s_add_i32 s0, s2, s9
	v_add_u32_e32 v142, s0, v146
	v_readlane_b32 s0, v253, 18
	v_ashrrev_i32_e32 v143, 31, v142
	v_readlane_b32 s1, v253, 19
	v_lshl_add_u32 v146, v146, 2, s8
	s_nop 0
	v_lshl_add_u64 v[150:151], v[142:143], 4, s[0:1]
	global_load_dwordx4 v[138:141], v[150:151], off
	global_load_dwordx4 v[164:167], v[150:151], off offset:2048
	s_mov_b32 s0, 0x3a800000
	s_waitcnt vmcnt(1)
	v_mov_b32_e32 v144, v139
	v_mov_b32_e32 v145, v140
	v_mov_b32_e32 v139, v141
	v_pk_add_f32 v[144:145], v[144:145], v[138:139]
	s_waitcnt vmcnt(0)
	v_mov_b32_e32 v142, v165
	v_mov_b32_e32 v143, v166
	v_mov_b32_e32 v165, v167
	v_pk_add_f32 v[138:139], v[142:143], v[164:165]
	v_mov_b32_e32 v141, v144
	v_mov_b32_e32 v140, v138
	v_mov_b32_e32 v144, v139
	v_pk_add_f32 v[138:139], v[140:141], v[144:145]
	s_nop 0
	v_pk_fma_f32 v[138:139], v[138:139], s[0:1], v[170:171] op_sel_hi:[1,0,0]
	s_mov_b32 s0, 0x800000
	v_mul_f32_e32 v140, 0x4b800000, v139
	v_cmp_gt_f32_e32 vcc, s0, v138
	v_cmp_gt_f32_e64 s[0:1], s0, v139
	s_nop 1
	v_cndmask_b32_e64 v139, v139, v140, s[0:1]
	v_rsq_f32_e32 v139, v139
	s_nop 0
	v_mul_f32_e32 v140, 0x45800000, v139
	v_cndmask_b32_e64 v139, v139, v140, s[0:1]
	v_mul_f32_e32 v140, 0x4b800000, v138
	v_cndmask_b32_e32 v138, v138, v140, vcc
	v_rsq_f32_e32 v138, v138
	s_mov_b64 s[0:1], 0
	v_mul_f32_e32 v140, 0x45800000, v138
	v_cndmask_b32_e32 v138, v138, v140, vcc
	ds_write2st64_b32 v146, v139, v138 offset1:1
